# P0 order mixing keyed on workgroup id bit 3 (within each XCD) instead of bit 0 (XCD parity)
# baseline (speedup 1.0000x reference)
; #define LAS __attribute__((address_space(3)))
; __global__ void __launch_bounds__(512, 2) hybrid_fwd(Args args) {
;     ...
;     unsigned char* ws = args.ws; unsigned char* ob = (unsigned char*)args.out;
;     float* SS0 = (float*)(ws + WS_CTL + CTL_SS0); float* SS1 = (float*)(ws + WS_CTL + CTL_SS1); float* SS2 = (float*)(ws + WS_CTL + CTL_SS2); float* F0 = (float*)(ws + WS_CTL + CTL_F0); unsigned* PCNT = (unsigned*)(ws + WS_CTL + CTL_CNT);
;     bf16* WIN = (bf16*)(ws + WS_WIN); bf16* WBA = (bf16*)(ws + WS_WBA); bf16* WBH = (bf16*)(ws + WS_WBH); bf16* WO = (bf16*)(ws + WS_WO); bf16* WGU = (bf16*)(ws + WS_WGU); bf16* WD = (bf16*)(ws + WS_WD);
;     bf16* XB = (bf16*)(ws + WS_XB); bf16* Qb = (bf16*)(ws + WS_Q); bf16* Kb = (bf16*)(ws + WS_K); bf16* VT = (bf16*)(ws + WS_VT);
;     bf16* FRP = (bf16*)(ws + WS_FRP); bf16* FRS = (bf16*)(ws + WS_FRS); bf16* M1 = (bf16*)(ws + WS_M1); bf16* Hb = (bf16*)(ws + WS_H);
;     bf16* HY = (bf16*)(ob + OUT_HY); bf16* UT = (bf16*)(ob + OUT_UT); bf16* M2 = (bf16*)(ob + OUT_M2);
;     const int lo = args.ph_lo, hi = args.ph_hi;
;     const int gw = F.bid * 8 + F.wave, NGW = F.G * 8;
;     ...
;     DUP_BEGIN(0) if (IN(0)) {
;         LAS float* scr = (LAS float*)(F.lds + F.wave * 16384);
;         const float* nmix = args.in[2]; const float* nffn = args.in[19];
;         constexpr int I_IN = 16 * 160, I_BR = 8 * 32, I_O = 16 * 32, I_G = 16 * 88, I_D = 44 * 32;
;         constexpr int NITEMS = I_IN + 2 * I_BR + I_O + 2 * I_G + I_D;
;         if (sub & 1) for (int it = gw; it < NITEMS; it += NGW) {
.LBB0_17:
	s_load_dwordx16 s[16:31], s[0:1], 0x40
	s_load_dwordx16 s[36:51], s[0:1], 0x80
	s_lshr_b32 s58, s12, 6
	v_and_b32_e32 v148, 63, v150
	s_waitcnt lgkmcnt(0)
	v_writelane_b32 v246, s36, 2
	s_nop 1
	v_writelane_b32 v246, s37, 3
	v_writelane_b32 v246, s38, 4
	v_writelane_b32 v246, s39, 5
	v_writelane_b32 v246, s40, 6
	v_writelane_b32 v246, s41, 7
	v_writelane_b32 v246, s42, 8
	v_writelane_b32 v246, s43, 9
	v_writelane_b32 v246, s44, 10
	v_writelane_b32 v246, s45, 11
	v_writelane_b32 v246, s46, 12
	v_writelane_b32 v246, s47, 13
	v_writelane_b32 v246, s48, 14
	v_writelane_b32 v246, s49, 15
	v_writelane_b32 v246, s50, 16
	v_writelane_b32 v246, s51, 17
	s_add_u32 s46, s82, 0x20000
	s_addc_u32 s47, s83, 0
	s_add_u32 s34, s82, 0x60000
	s_addc_u32 s35, s83, 0
	s_add_u32 s0, s82, 0x64000
	s_addc_u32 s1, s83, 0
	v_writelane_b32 v246, s12, 18
	s_add_u32 s10, s82, 0x100000
	v_writelane_b32 v246, s0, 19
	s_addc_u32 s11, s83, 0
	s_nop 0
	v_writelane_b32 v246, s1, 20
	s_add_u32 s0, s82, 0xb00000
	s_addc_u32 s1, s83, 0
	v_writelane_b32 v246, s0, 21
	s_nop 1
	v_writelane_b32 v246, s1, 22
	s_add_u32 s0, s82, 0xc00000
	s_addc_u32 s1, s83, 0
	v_writelane_b32 v246, s0, 23
	s_nop 1
	v_writelane_b32 v246, s1, 24
	s_add_u32 s0, s82, 0xd00000
	s_addc_u32 s1, s83, 0
	s_add_u32 s90, s82, 0xf00000
	v_writelane_b32 v246, s0, 25
	s_addc_u32 s91, s83, 0
	s_nop 0
	v_writelane_b32 v246, s1, 26
	s_add_u32 s0, s82, 0x1a00000
	s_addc_u32 s1, s83, 0
	s_add_u32 s92, s82, 0x2000000
	s_addc_u32 s93, s83, 0
	v_writelane_b32 v246, s0, 27
	s_add_u32 s40, s82, 0xc800000
	s_addc_u32 s41, s83, 0
	v_writelane_b32 v246, s1, 28
	s_lshl_b32 s0, s33, 3
	s_add_i32 s86, s58, s0
	s_lshl_b32 s88, s89, 3
	s_cmp_lt_i32 s84, 1
	s_cselect_b64 s[0:1], -1, 0
	s_cmp_gt_i32 s85, 0
	s_cselect_b64 s[2:3], -1, 0
	s_and_b64 s[12:13], s[0:1], s[2:3]
	s_andn2_b64 vcc, exec, s[12:13]
	v_writelane_b32 v246, s58, 29
	s_mov_b32 s101, 1
	s_cbranch_vccnz .LBB0_361
	s_mov_b32 s101, 0
	s_bitcmp1_b32 s33, 3
	s_cbranch_scc1 .LBB0_172

; __global__ void __launch_bounds__(512, 2) hybrid_fwd(Args args) {
;     ...
;         if (sub & 1) for (int it = gw; it < NITEMS; it += NGW) {
;             int r = it;
;             if (r < I_IN) { p0_transpose_item(args.in[3], 1024, 5120, WIN, nmix, 0, scr, r, F.lane); continue; } r -= I_IN;
;             if (r < I_BR) { p0_transpose_item(args.in[16], 512, 1024, WBA, nullptr, 0, scr, r, F.lane); continue; } r -= I_BR;
;             if (r < I_BR) { p0_transpose_item(args.in[17], 512, 1024, WBH, nullptr, 0, scr, r, F.lane); continue; } r -= I_BR;
;             if (r < I_O) { p0_transpose_item(args.in[18], 1024, 1024, WO, nullptr, 0, scr, r, F.lane); continue; } r -= I_O;
;             if (r < I_G) { p0_transpose_item(args.in[20], 1024, DFF, WGU, nffn, 1, scr, r, F.lane); continue; } r -= I_G;
;             if (r < I_G) { p0_transpose_item(args.in[21], 1024, DFF, WGU, nffn, 2, scr, r, F.lane); continue; } r -= I_G;
;             p0_transpose_item(args.in[22], DFF, 1024, WD, nullptr, 0, scr, r, F.lane);
;         }
;         if (sub & 2) for (int m = gw; m < MTOK; m += 4 * NGW) {
.LBB0_361:
	s_cmp_lg_u32 s101, 0
	s_cbranch_scc1 .Lp0_done
	s_bitcmp1_b32 s33, 3
	s_cbranch_scc0 .Lp0_done
	s_mov_b32 s101, 1
	s_branch .Lp0_a_start
